# P2 attention NOMAX loop: row-sum serial chain of 32 dependent v_add_f32 split into two independent even/odd chains (31 adds), on top of P1 LDS tables
# speedup vs baseline: 1.0254x; 1.0254x over previous
.LBB0_1097:
	s_mov_b32 s7, s89
	v_mov_b64_e32 v[226:227], v[100:101]
	s_mov_b32 s88, s38
	v_mov_b64_e32 v[228:229], v[98:99]
	s_mov_b32 s37, s87
	v_add_u32_e32 v198, s36, v233
	ds_read_b64_tr_b16 v[200:201], v198 offset:24576
	ds_read_b64_tr_b16 v[202:203], v198 offset:25088
	v_add_f32_e32 v98, v84, v82
	v_add_f32_e32 v99, v85, v83
	v_add_f32_e32 v98, v86, v98
	v_add_f32_e32 v99, v87, v99
	v_cvt_pk_bf16_f32 v158, v82, v83
	v_cvt_pk_bf16_f32 v159, v84, v85
	s_waitcnt lgkmcnt(9)
	v_mfma_f32_32x32x16_bf16 v[114:129], v[190:193], v[130:133], v[50:65]
	ds_read_b64_tr_b16 v[82:83], v198 offset:28672
	ds_read_b64_tr_b16 v[84:85], v198 offset:29184
	v_add_f32_e32 v98, v88, v98
	v_add_f32_e32 v99, v89, v99
	v_add_f32_e32 v146, v90, v98
	v_add_f32_e32 v147, v91, v99
	s_waitcnt lgkmcnt(10)
	v_mfma_f32_32x32x16_bf16 v[98:113], v[186:189], v[130:133], v[50:65]
	v_cvt_pk_bf16_f32 v160, v86, v87
	v_cvt_pk_bf16_f32 v161, v88, v89
	ds_read_b64_tr_b16 v[86:87], v198 offset:25600
	ds_read_b64_tr_b16 v[88:89], v198 offset:26112
	v_add_f32_e32 v146, v92, v146
	v_add_f32_e32 v147, v93, v147
	v_add_f32_e32 v146, v94, v146
	v_add_f32_e32 v147, v95, v147
	v_cvt_pk_bf16_f32 v154, v90, v91
	v_cvt_pk_bf16_f32 v155, v92, v93
	s_waitcnt lgkmcnt(11)
	v_mfma_f32_32x32x16_bf16 v[114:129], v[182:185], v[134:137], v[114:129]
	ds_read_b64_tr_b16 v[90:91], v198 offset:29696
	ds_read_b64_tr_b16 v[92:93], v198 offset:30208
	s_waitcnt lgkmcnt(12)
	v_mfma_f32_32x32x16_bf16 v[98:113], v[178:181], v[134:137], v[98:113]
	v_add_f32_e32 v146, v96, v146
	v_add_f32_e32 v147, v97, v147
	v_add_f32_e32 v146, v66, v146
	v_add_f32_e32 v147, v67, v147
	v_cvt_pk_bf16_f32 v156, v94, v95
	v_cvt_pk_bf16_f32 v157, v96, v97
	ds_read_b64_tr_b16 v[94:95], v198 offset:26624
	ds_read_b64_tr_b16 v[96:97], v198 offset:27136
	v_add_f32_e32 v146, v68, v146
	v_add_f32_e32 v147, v69, v147
	v_add_f32_e32 v146, v70, v146
	v_add_f32_e32 v147, v71, v147
	v_cvt_pk_bf16_f32 v150, v66, v67
	v_cvt_pk_bf16_f32 v151, v68, v69
	s_waitcnt lgkmcnt(13)
	v_mfma_f32_32x32x16_bf16 v[114:129], v[174:177], v[138:141], v[114:129]
	ds_read_b64_tr_b16 v[66:67], v198 offset:30720
	ds_read_b64_tr_b16 v[68:69], v198 offset:31232
	s_waitcnt lgkmcnt(14)
	v_mfma_f32_32x32x16_bf16 v[98:113], v[170:173], v[138:141], v[98:113]
	v_add_f32_e32 v146, v72, v146
	v_add_f32_e32 v147, v73, v147
	v_add_f32_e32 v146, v74, v146
	v_add_f32_e32 v147, v75, v147
	v_cvt_pk_bf16_f32 v152, v70, v71
	v_cvt_pk_bf16_f32 v153, v72, v73
	ds_read_b64_tr_b16 v[70:71], v198 offset:27648
	ds_read_b64_tr_b16 v[72:73], v198 offset:28160
	v_add_f32_e32 v146, v76, v146
	v_add_f32_e32 v147, v77, v147
	v_add_f32_e32 v170, v78, v146
	v_add_f32_e32 v171, v79, v147
	v_cvt_pk_bf16_f32 v146, v74, v75
	v_cvt_pk_bf16_f32 v147, v76, v77
	s_waitcnt lgkmcnt(14)
	v_mfma_f32_32x32x16_bf16 v[114:129], v[166:169], v[142:145], v[114:129]
	ds_read_b64_tr_b16 v[74:75], v198 offset:31744
	ds_read_b64_tr_b16 v[76:77], v198 offset:32256
	v_mfma_f32_32x32x16_bf16 v[98:113], v[162:165], v[142:145], v[98:113]
	v_add_f32_e32 v148, v80, v170
	v_add_f32_e32 v149, v81, v171
	v_add_f32_e32 v198, v148, v149
	v_cvt_pk_bf16_f32 v148, v78, v79
	v_cvt_pk_bf16_f32 v149, v80, v81
	v_lshl_add_u64 v[78:79], v[196:197], 0, s[24:25]
	s_add_i32 s0, s87, s84
	s_mov_b32 s1, m0
	s_mov_b32 m0, s0
	s_nop 0
	global_load_lds_dwordx4 v[78:79], off
	s_mov_b32 m0, s1
	v_lshl_add_u64 v[78:79], v[194:195], 0, s[24:25]
	s_add_i32 s0, s89, s8
	s_mov_b32 s1, m0
	s_mov_b32 m0, s0
	s_nop 0
	global_load_lds_dwordx4 v[78:79], off
	s_mov_b32 m0, s1
	s_waitcnt lgkmcnt(14)
	v_mfma_f32_32x32x16_bf16 v[18:33], v[158:161], v[200:203], v[18:33]
	v_exp_f32_e32 v114, v114
	v_exp_f32_e32 v115, v115
	v_exp_f32_e32 v116, v116
	v_exp_f32_e32 v117, v117
	s_waitcnt lgkmcnt(12)
	v_mfma_f32_32x32x16_bf16 v[34:49], v[158:161], v[82:85], v[34:49]
	v_exp_f32_e32 v118, v118
	v_exp_f32_e32 v119, v119
	v_exp_f32_e32 v120, v120
	v_exp_f32_e32 v121, v121
	v_add_u32_e32 v82, s7, v232
	ds_read_b128 v[78:81], v82
	ds_read_b128 v[162:165], v82 offset:512
	s_waitcnt lgkmcnt(12)
	v_mfma_f32_32x32x16_bf16 v[18:33], v[154:157], v[86:89], v[18:33]
	v_exp_f32_e32 v122, v122
	v_exp_f32_e32 v123, v123
	v_exp_f32_e32 v124, v124
	v_exp_f32_e32 v125, v125
	ds_read_b128 v[166:169], v82 offset:2048
	ds_read_b128 v[170:173], v82 offset:2560
	s_waitcnt lgkmcnt(12)
	v_mfma_f32_32x32x16_bf16 v[34:49], v[154:157], v[90:93], v[34:49]
	v_exp_f32_e32 v126, v126
	v_exp_f32_e32 v127, v127
	v_exp_f32_e32 v128, v128
	v_exp_f32_e32 v129, v129
	ds_read_b128 v[174:177], v82 offset:4096
	ds_read_b128 v[178:181], v82 offset:4608
	s_waitcnt lgkmcnt(12)
	v_mfma_f32_32x32x16_bf16 v[18:33], v[150:153], v[94:97], v[18:33]
	v_exp_f32_e32 v98, v98
	v_exp_f32_e32 v99, v99
	v_exp_f32_e32 v100, v100
	v_exp_f32_e32 v101, v101
	ds_read_b128 v[182:185], v82 offset:6144
	ds_read_b128 v[186:189], v82 offset:6656
	s_waitcnt lgkmcnt(12)
	v_mfma_f32_32x32x16_bf16 v[34:49], v[150:153], v[66:69], v[34:49]
	v_exp_f32_e32 v102, v102
	v_exp_f32_e32 v103, v103
	v_exp_f32_e32 v104, v104
	v_exp_f32_e32 v105, v105
	s_waitcnt lgkmcnt(10)
	v_mfma_f32_32x32x16_bf16 v[18:33], v[146:149], v[70:73], v[18:33]
	v_exp_f32_e32 v106, v106
	v_exp_f32_e32 v107, v107
	v_exp_f32_e32 v108, v108
	v_exp_f32_e32 v109, v109
	s_waitcnt lgkmcnt(8)
	v_mfma_f32_32x32x16_bf16 v[34:49], v[146:149], v[74:77], v[34:49]
	v_exp_f32_e32 v110, v110
	v_exp_f32_e32 v111, v111
	v_exp_f32_e32 v112, v112
	v_exp_f32_e32 v113, v113
	s_waitcnt vmcnt(2) lgkmcnt(0)
	s_barrier
; #define WAIT_BAR(N) asm volatile("s_waitcnt vmcnt(" #N ") lgkmcnt(0)\n\ts_barrier":::"memory")
;   #define RESC() do{ if(resc){ asm volatile("s_waitcnt lgkmcnt(0)":::"memory"); \
;       _Pragma("unroll") for(int d_=0;d_<2;++d_) _Pragma("unroll") for(int r=0;r<16;++r)o[d_][r]*=wsf[crow(r,hi)]; } }while(0)
;   #define ROT() do{sl_prev=sl_cur;sl_cur=sl_next;sl_next=(sl_next==(NSLOT-1)*SLOTB)?0:sl_next+SLOTB;}while(0)
; template<int THRL,bool NOMAX> __device__ __forceinline__ void attn_unit(long rowbase,int NT,int h,int qb,const bf16*Q,const bf16*__restrict__ Kh,const bf16*__restrict__ Vh,bf16*O,char*shm,
;     bool first,bool has_next,long n_rowbase,int n_h,int n_qb,const bf16*__restrict__ n_Kh,bf16x8 (&qr)[4]){
;     ...
;   int t=1;
;     ...
;   for(;t+5<NT;t+=2){
;     STEP(pB0,pB1,pA0,pA1,t,true,true,true);     WAIT_BAR(2); RESC(); ROT();
;     STEP(pA0,pA1,pB0,pB1,t+1,true,true,true);   WAIT_BAR(2); RESC(); ROT();
	s_add_i32 s0, s89, 0x2000
	s_cmpk_lg_i32 s89, 0x4000
	s_cselect_b32 s87, s0, 0
	v_add_u32_e32 v199, s37, v233
	ds_read_b64_tr_b16 v[190:191], v199 offset:24576
	ds_read_b64_tr_b16 v[192:193], v199 offset:25088
	s_waitcnt lgkmcnt(9)
	v_mfma_f32_32x32x16_bf16 v[82:97], v[78:81], v[130:133], v[50:65]
	v_add_f32_e32 v66, v116, v114
	v_add_f32_e32 v67, v117, v115
	v_add_f32_e32 v66, v118, v66
	v_add_f32_e32 v67, v119, v67
	v_cvt_pk_bf16_f32 v158, v114, v115
	v_cvt_pk_bf16_f32 v159, v116, v117
	ds_read_b64_tr_b16 v[114:115], v199 offset:28672
	ds_read_b64_tr_b16 v[116:117], v199 offset:29184
	v_add_f32_e32 v66, v120, v66
	v_add_f32_e32 v67, v121, v67
	v_add_f32_e32 v146, v122, v66
	v_add_f32_e32 v147, v123, v67
	s_waitcnt lgkmcnt(10)
	v_mfma_f32_32x32x16_bf16 v[66:81], v[162:165], v[130:133], v[50:65]
	v_cvt_pk_bf16_f32 v160, v118, v119
	v_cvt_pk_bf16_f32 v161, v120, v121
	ds_read_b64_tr_b16 v[118:119], v199 offset:25600
	ds_read_b64_tr_b16 v[120:121], v199 offset:26112
	s_waitcnt lgkmcnt(11)
	v_mfma_f32_32x32x16_bf16 v[82:97], v[166:169], v[134:137], v[82:97]
	v_add_f32_e32 v146, v124, v146
	v_add_f32_e32 v147, v125, v147
	v_add_f32_e32 v146, v126, v146
	v_add_f32_e32 v147, v127, v147
	v_cvt_pk_bf16_f32 v154, v122, v123
	v_cvt_pk_bf16_f32 v155, v124, v125
	ds_read_b64_tr_b16 v[122:123], v199 offset:29696
	ds_read_b64_tr_b16 v[124:125], v199 offset:30208
	s_waitcnt lgkmcnt(12)
	v_mfma_f32_32x32x16_bf16 v[66:81], v[170:173], v[134:137], v[66:81]
	v_add_f32_e32 v146, v128, v146
	v_add_f32_e32 v147, v129, v147
	v_add_f32_e32 v146, v98, v146
	v_add_f32_e32 v147, v99, v147
	v_cvt_pk_bf16_f32 v156, v126, v127
	v_cvt_pk_bf16_f32 v157, v128, v129
	ds_read_b64_tr_b16 v[126:127], v199 offset:26624
	ds_read_b64_tr_b16 v[128:129], v199 offset:27136
	s_waitcnt lgkmcnt(13)
	v_mfma_f32_32x32x16_bf16 v[82:97], v[174:177], v[138:141], v[82:97]
	v_add_f32_e32 v146, v100, v146
	v_add_f32_e32 v147, v101, v147
	v_add_f32_e32 v146, v102, v146
	v_add_f32_e32 v147, v103, v147
	v_cvt_pk_bf16_f32 v150, v98, v99
	v_cvt_pk_bf16_f32 v151, v100, v101
	ds_read_b64_tr_b16 v[98:99], v199 offset:30720
	ds_read_b64_tr_b16 v[100:101], v199 offset:31232
	s_waitcnt lgkmcnt(14)
	v_mfma_f32_32x32x16_bf16 v[66:81], v[178:181], v[138:141], v[66:81]
	v_add_f32_e32 v146, v104, v146
	v_add_f32_e32 v147, v105, v147
	v_add_f32_e32 v146, v106, v146
	v_add_f32_e32 v147, v107, v147
	v_cvt_pk_bf16_f32 v152, v102, v103
	v_cvt_pk_bf16_f32 v153, v104, v105
	ds_read_b64_tr_b16 v[102:103], v199 offset:27648
	ds_read_b64_tr_b16 v[104:105], v199 offset:28160
	s_waitcnt lgkmcnt(14)
	v_mfma_f32_32x32x16_bf16 v[82:97], v[182:185], v[142:145], v[82:97]
	v_add_f32_e32 v146, v108, v146
	v_add_f32_e32 v147, v109, v147
	v_add_f32_e32 v162, v110, v146
	v_add_f32_e32 v163, v111, v147
	v_cvt_pk_bf16_f32 v146, v106, v107
	v_cvt_pk_bf16_f32 v147, v108, v109
	ds_read_b64_tr_b16 v[106:107], v199 offset:31744
	ds_read_b64_tr_b16 v[108:109], v199 offset:32256
	v_mfma_f32_32x32x16_bf16 v[66:81], v[186:189], v[142:145], v[66:81]
	v_add_f32_e32 v148, v112, v162
	v_add_f32_e32 v149, v113, v163
	v_add_f32_e32 v199, v148, v149
	v_cvt_pk_bf16_f32 v148, v110, v111
	v_cvt_pk_bf16_f32 v149, v112, v113
	s_add_i32 s0, s89, s84
	s_mov_b32 s1, m0
	s_mov_b32 m0, s0
	s_nop 0
	global_load_lds_dwordx4 v[196:197], off
	s_mov_b32 m0, s1
	s_add_i32 s0, s87, s8
	s_mov_b32 s1, m0
	s_mov_b32 m0, s0
	s_nop 0
	global_load_lds_dwordx4 v[194:195], off
	s_mov_b32 m0, s1
	s_waitcnt lgkmcnt(14)
	v_mfma_f32_32x32x16_bf16 v[18:33], v[158:161], v[190:193], v[18:33]
	v_exp_f32_e32 v82, v82
	v_exp_f32_e32 v83, v83
	v_exp_f32_e32 v84, v84
	v_exp_f32_e32 v85, v85
	s_waitcnt lgkmcnt(12)
	v_mfma_f32_32x32x16_bf16 v[34:49], v[158:161], v[114:117], v[34:49]
	v_exp_f32_e32 v86, v86
	v_exp_f32_e32 v87, v87
	v_exp_f32_e32 v88, v88
	v_exp_f32_e32 v89, v89
	v_add_u32_e32 v110, s87, v232
	ds_read_b128 v[190:193], v110
	ds_read_b128 v[186:189], v110 offset:512
	s_waitcnt lgkmcnt(12)
	v_mfma_f32_32x32x16_bf16 v[18:33], v[154:157], v[118:121], v[18:33]
	v_exp_f32_e32 v90, v90
	v_exp_f32_e32 v91, v91
	v_exp_f32_e32 v92, v92
	v_exp_f32_e32 v93, v93
	ds_read_b128 v[182:185], v110 offset:2048
	ds_read_b128 v[178:181], v110 offset:2560
	s_waitcnt lgkmcnt(12)
	v_mfma_f32_32x32x16_bf16 v[34:49], v[154:157], v[122:125], v[34:49]
	v_exp_f32_e32 v94, v94
	v_exp_f32_e32 v95, v95
	v_exp_f32_e32 v96, v96
	v_exp_f32_e32 v97, v97
	ds_read_b128 v[174:177], v110 offset:4096
	ds_read_b128 v[170:173], v110 offset:4608
	s_waitcnt lgkmcnt(12)
	v_mfma_f32_32x32x16_bf16 v[18:33], v[150:153], v[126:129], v[18:33]
	v_exp_f32_e32 v66, v66
	v_exp_f32_e32 v67, v67
	v_exp_f32_e32 v68, v68
	v_exp_f32_e32 v69, v69
	ds_read_b128 v[166:169], v110 offset:6144
	ds_read_b128 v[162:165], v110 offset:6656
	s_waitcnt lgkmcnt(12)
	v_mfma_f32_32x32x16_bf16 v[34:49], v[150:153], v[98:101], v[34:49]
	v_exp_f32_e32 v70, v70
	v_exp_f32_e32 v71, v71
	v_exp_f32_e32 v72, v72
	v_exp_f32_e32 v73, v73
	s_waitcnt lgkmcnt(10)
	v_mfma_f32_32x32x16_bf16 v[18:33], v[146:149], v[102:105], v[18:33]
	v_exp_f32_e32 v74, v74
	v_exp_f32_e32 v75, v75
	v_exp_f32_e32 v76, v76
	v_exp_f32_e32 v77, v77
	s_waitcnt lgkmcnt(8)
	v_mfma_f32_32x32x16_bf16 v[34:49], v[146:149], v[106:109], v[34:49]
	v_exp_f32_e32 v78, v78
	v_exp_f32_e32 v79, v79
	v_exp_f32_e32 v80, v80
	v_exp_f32_e32 v81, v81
	s_add_i32 s0, s87, 0x2000
	s_waitcnt vmcnt(2) lgkmcnt(0)
	s_barrier
	s_cmpk_lg_i32 s87, 0x4000
	v_add_f32_e32 v102, v206, v198
	s_mov_b32 s36, s89
	s_cselect_b32 s89, s0, 0
	s_add_i32 s6, s6, 2
	s_add_i32 s38, s38, 2
	v_lshl_add_u64 v[194:195], v[194:195], 0, s[14:15]
	v_lshl_add_u64 v[196:197], v[196:197], 0, s[14:15]
	v_lshl_add_u64 v[100:101], v[226:227], 0, s[14:15]
	v_lshl_add_u64 v[98:99], v[228:229], 0, s[14:15]
	s_cmp_ge_u32 s6, s82
	v_add_f32_e32 v206, v102, v199
	s_cbranch_scc0 .LBB0_1097
	s_add_i32 s0, s6, -4
	s_cmp_ge_u32 s0, s82
	s_cbranch_scc1 .LBB0_1132
	s_add_i32 s90, s6, -5
